# accumulator re-init between GEMM units: 64 v_mov_b64 behind a keep-branch instead of 128 selects / 128 v_mov_b32
# speedup vs baseline: 1.0122x; 1.0122x over previous
; template <bool F8 = false, class Sched, class Epi>
; __device__ __forceinline__ void gemm_phase(LAS unsigned char* lds, const Sched& S, const Epi& E) {
;     ...
;     f32x4 acc[2][2][4][2];
; #pragma unroll
;     for (int a = 0; a < 2; ++a)
; #pragma unroll
;         for (int b = 0; b < 2; ++b)
; #pragma unroll
;             for (int m = 0; m < 4; ++m)
; #pragma unroll
;                 for (int n = 0; n < 2; ++n) acc[a][b][m][n] = (f32x4){0.f, 0.f, 0.f, 0.f};
.LBB0_64:
	s_mov_b32 s28, s44
	s_mov_b32 s29, s66
	s_mov_b32 s30, s50
	s_mov_b64 s[8:9], s[16:17]
	s_mov_b64 s[12:13], s[18:19]
	v_mov_b64_e32 v[34:35], 0
	v_mov_b64_e32 v[36:37], 0
	v_mov_b64_e32 v[38:39], 0
	v_mov_b64_e32 v[40:41], 0
	v_mov_b64_e32 v[42:43], 0
	v_mov_b64_e32 v[44:45], 0
	v_mov_b64_e32 v[46:47], 0
	v_mov_b64_e32 v[48:49], 0
	v_mov_b64_e32 v[50:51], 0
	v_mov_b64_e32 v[52:53], 0
	v_mov_b64_e32 v[54:55], 0
	v_mov_b64_e32 v[56:57], 0
	v_mov_b64_e32 v[58:59], 0
	v_mov_b64_e32 v[60:61], 0
	v_mov_b64_e32 v[62:63], 0
	v_mov_b64_e32 v[64:65], 0
	v_mov_b64_e32 v[66:67], 0
	v_mov_b64_e32 v[68:69], 0
	v_mov_b64_e32 v[70:71], 0
	v_mov_b64_e32 v[72:73], 0
	v_mov_b64_e32 v[74:75], 0
	v_mov_b64_e32 v[76:77], 0
	v_mov_b64_e32 v[78:79], 0
	v_mov_b64_e32 v[80:81], 0
	v_mov_b64_e32 v[82:83], 0
	v_mov_b64_e32 v[84:85], 0
	v_mov_b64_e32 v[86:87], 0
	v_mov_b64_e32 v[88:89], 0
	v_mov_b64_e32 v[90:91], 0
	v_mov_b64_e32 v[92:93], 0
	v_mov_b64_e32 v[94:95], 0
	v_mov_b64_e32 v[96:97], 0
	v_mov_b64_e32 v[98:99], 0
	v_mov_b64_e32 v[100:101], 0
	v_mov_b64_e32 v[102:103], 0
	v_mov_b64_e32 v[104:105], 0
	v_mov_b64_e32 v[106:107], 0
	v_mov_b64_e32 v[108:109], 0
	v_mov_b64_e32 v[110:111], 0
	v_mov_b64_e32 v[112:113], 0
	v_mov_b64_e32 v[114:115], 0
	v_mov_b64_e32 v[116:117], 0
	v_mov_b64_e32 v[118:119], 0
	v_mov_b64_e32 v[120:121], 0
	v_mov_b64_e32 v[122:123], 0
	v_mov_b64_e32 v[124:125], 0
	v_mov_b64_e32 v[126:127], 0
	v_mov_b64_e32 v[128:129], 0
	v_mov_b64_e32 v[130:131], 0
	v_mov_b64_e32 v[132:133], 0
	v_mov_b64_e32 v[134:135], 0
	v_mov_b64_e32 v[136:137], 0
	v_mov_b64_e32 v[138:139], 0
	v_mov_b64_e32 v[140:141], 0
	v_mov_b64_e32 v[142:143], 0
	v_mov_b64_e32 v[144:145], 0
	v_mov_b64_e32 v[146:147], 0
	v_mov_b64_e32 v[148:149], 0
	v_mov_b64_e32 v[150:151], 0
	v_mov_b64_e32 v[152:153], 0
	v_mov_b64_e32 v[154:155], 0
	v_mov_b64_e32 v[156:157], 0
	v_mov_b64_e32 v[158:159], 0
	v_mov_b64_e32 v[160:161], 0
	v_mov_b32_e32 v162, v175
	s_mov_b32 s67, s70
	s_andn2_b64 vcc, exec, s[20:21]
	v_mov_b32_e32 v164, v166
	s_cbranch_vccz .LBB0_112

; #define PG8_BAR __builtin_amdgcn_s_barrier()
; template <bool F8 = false, class Sched, class Epi>
; __device__ __forceinline__ void gemm_phase(LAS unsigned char* lds, const Sched& S, const Epi& E) {
;     ...
;         { const bool keep = Epi::keeps_acc(cur.kind);
; #pragma unroll
;         for (int a = 0; a < 2; ++a)
; #pragma unroll
;             for (int b = 0; b < 2; ++b)
; #pragma unroll
;                 for (int m = 0; m < 4; ++m)
; #pragma unroll
;                     for (int n = 0; n < 2; ++n)
; #pragma unroll
;                         for (int e = 0; e < 4; ++e) acc[a][b][m][n][e] = keep ? acc[a][b][m][n][e] : 0.f;
;         }
;         cur = nxt; cA = nA; cB = nB; cK2 = nK2; cvA = nvA; cvB = nvB; ch64 = nh64; chs = nhs; cbhs = nbhs; ++ui;
;         if (wr == 1) PG8_BAR;
.LBB0_224:
	s_and_b64 vcc, exec, s[6:7]
	s_cbranch_vccnz .Lacc_keep
	v_mov_b64_e32 v[0:1], 0
	v_mov_b64_e32 v[2:3], 0
	v_mov_b64_e32 v[4:5], 0
	v_mov_b64_e32 v[6:7], 0
	v_mov_b64_e32 v[8:9], 0
	v_mov_b64_e32 v[10:11], 0
	v_mov_b64_e32 v[12:13], 0
	v_mov_b64_e32 v[14:15], 0
	v_mov_b64_e32 v[16:17], 0
	v_mov_b64_e32 v[18:19], 0
	v_mov_b64_e32 v[20:21], 0
	v_mov_b64_e32 v[22:23], 0
	v_mov_b64_e32 v[24:25], 0
	v_mov_b64_e32 v[26:27], 0
	v_mov_b64_e32 v[28:29], 0
	v_mov_b64_e32 v[30:31], 0
	v_mov_b64_e32 v[36:37], 0
	v_mov_b64_e32 v[38:39], 0
	v_mov_b64_e32 v[40:41], 0
	v_mov_b64_e32 v[42:43], 0
	v_mov_b64_e32 v[44:45], 0
	v_mov_b64_e32 v[46:47], 0
	v_mov_b64_e32 v[48:49], 0
	v_mov_b64_e32 v[50:51], 0
	v_mov_b64_e32 v[52:53], 0
	v_mov_b64_e32 v[54:55], 0
	v_mov_b64_e32 v[56:57], 0
	v_mov_b64_e32 v[58:59], 0
	v_mov_b64_e32 v[60:61], 0
	v_mov_b64_e32 v[62:63], 0
	v_mov_b64_e32 v[64:65], 0
	v_mov_b64_e32 v[66:67], 0
	v_mov_b64_e32 v[68:69], 0
	v_mov_b64_e32 v[70:71], 0
	v_mov_b64_e32 v[72:73], 0
	v_mov_b64_e32 v[74:75], 0
	v_mov_b64_e32 v[76:77], 0
	v_mov_b64_e32 v[78:79], 0
	v_mov_b64_e32 v[80:81], 0
	v_mov_b64_e32 v[82:83], 0
	v_mov_b64_e32 v[84:85], 0
	v_mov_b64_e32 v[86:87], 0
	v_mov_b64_e32 v[88:89], 0
	v_mov_b64_e32 v[90:91], 0
	v_mov_b64_e32 v[92:93], 0
	v_mov_b64_e32 v[94:95], 0
	v_mov_b64_e32 v[96:97], 0
	v_mov_b64_e32 v[98:99], 0
	v_mov_b64_e32 v[100:101], 0
	v_mov_b64_e32 v[102:103], 0
	v_mov_b64_e32 v[104:105], 0
	v_mov_b64_e32 v[106:107], 0
	v_mov_b64_e32 v[108:109], 0
	v_mov_b64_e32 v[110:111], 0
	v_mov_b64_e32 v[112:113], 0
	v_mov_b64_e32 v[114:115], 0
	v_mov_b64_e32 v[116:117], 0
	v_mov_b64_e32 v[118:119], 0
	v_mov_b64_e32 v[120:121], 0
	v_mov_b64_e32 v[122:123], 0
	v_mov_b64_e32 v[124:125], 0
	v_mov_b64_e32 v[126:127], 0
	v_mov_b64_e32 v[128:129], 0
	v_mov_b64_e32 v[130:131], 0
.Lacc_keep:
	s_mov_b32 s70, s27
	s_mov_b32 s37, s28
	s_mov_b32 s34, s26
	s_mov_b64 s[66:67], s[2:3]
	s_mov_b64 s[42:43], s[20:21]
	s_mov_b64 s[14:15], s[22:23]
	s_andn2_b64 vcc, exec, s[84:85]
	s_cbranch_vccnz .LBB0_382
	s_branch .LBB0_427
